# v38 + FF1 epilogues not aligned between the two wave halves (leading half's epilogue overlaps the trailing half's last MFMA block)
# speedup vs baseline: 1.0066x; 1.0066x over previous
.LBB0_571:
	v_mov_b32_e32 v161, v164
	v_mov_b32_e32 v128, v165
	s_lshl_b32 s17, s72, 8
	s_or_b32 s17, s17, s66
	v_lshlrev_b32_e32 v160, 3, v128
	v_add_u32_e32 v128, s17, v160
	s_lshl_b32 s17, s26, 8
	s_and_b32 s28, s17, 0xfffff000
	s_ashr_i32 s29, s28, 31
	s_lshl_b64 s[28:29], s[28:29], 2
	s_add_u32 s28, s59, s28
	s_addc_u32 s29, s61, s29
	v_ashrrev_i32_e32 v129, 31, v128
	v_lshl_add_u64 v[128:129], v[128:129], 2, s[28:29]
	global_load_dwordx4 v[140:143], v[128:129], off
	global_load_dwordx4 v[136:139], v[128:129], off offset:16
	global_load_dwordx4 v[132:135], v[128:129], off offset:512
	s_nop 0
	global_load_dwordx4 v[128:131], v[128:129], off offset:528
	v_add_u32_e32 v162, s57, v161
	v_lshl_add_u32 v170, v162, 2, 0
	s_lshl_b32 s17, s72, 3
	v_add_u32_e32 v170, 0x22400, v170
	s_or_b32 s28, s17, s56
	s_ashr_i32 s27, s26, 31
	ds_read2_b32 v[172:173], v170 offset1:16
	s_ashr_i32 s29, s28, 31
	s_lshl_b64 s[26:27], s[26:27], 21
	s_lshl_b64 s[28:29], s[28:29], 14
	s_add_u32 s17, s64, s26
	s_addc_u32 s19, s65, s27
	v_ashrrev_i32_e32 v163, 31, v162
	s_add_u32 s26, s17, s28
	v_lshlrev_b64 v[162:163], 6, v[162:163]
	s_addc_u32 s27, s19, s29
	v_ashrrev_i32_e32 v161, 31, v160
	v_lshl_add_u64 v[162:163], s[26:27], 0, v[162:163]
	s_waitcnt lgkmcnt(0)
	v_mov_b32_e32 v174, v173
	v_lshl_add_u64 v[160:161], v[160:161], 1, v[162:163]
	v_add_co_u32_e32 v162, vcc, s49, v160
	s_waitcnt vmcnt(0)
	v_pk_fma_f32 v[126:127], v[126:127], v[172:173], v[142:143] op_sel_hi:[1,0,1]
	v_pk_fma_f32 v[124:125], v[124:125], v[172:173], v[140:141] op_sel_hi:[1,0,1]
	v_pk_fma_f32 v[122:123], v[122:123], v[172:173], v[138:139] op_sel_hi:[1,0,1]
	v_pk_fma_f32 v[120:121], v[120:121], v[172:173], v[136:137] op_sel_hi:[1,0,1]
	v_pk_fma_f32 v[110:111], v[110:111], v[172:173], v[134:135] op_sel_hi:[1,0,1]
	v_pk_fma_f32 v[108:109], v[108:109], v[172:173], v[132:133] op_sel_hi:[1,0,1]
	v_pk_fma_f32 v[106:107], v[106:107], v[172:173], v[130:131] op_sel_hi:[1,0,1]
	v_pk_fma_f32 v[104:105], v[104:105], v[172:173], v[128:129] op_sel_hi:[1,0,1]
	v_max_f32_e32 v124, 0, v124
	v_max_f32_e32 v120, 0, v120
	v_max_f32_e32 v125, 0, v125
	v_max_f32_e32 v121, 0, v121
	v_max_f32_e32 v126, 0, v126
	v_max_f32_e32 v122, 0, v122
	v_max_f32_e32 v127, 0, v127
	v_max_f32_e32 v123, 0, v123
	v_max_f32_e32 v108, 0, v108
	v_max_f32_e32 v104, 0, v104
	v_max_f32_e32 v109, 0, v109
	v_max_f32_e32 v105, 0, v105
	v_max_f32_e32 v110, 0, v110
	v_max_f32_e32 v106, 0, v106
	v_max_f32_e32 v111, 0, v111
	v_max_f32_e32 v107, 0, v107
	v_pk_mul_f32 v[124:125], v[124:125], v[124:125]
	v_pk_mul_f32 v[120:121], v[120:121], v[120:121]
	v_pk_mul_f32 v[126:127], v[126:127], v[126:127]
	v_pk_mul_f32 v[122:123], v[122:123], v[122:123]
	v_pk_mul_f32 v[108:109], v[108:109], v[108:109]
	v_pk_mul_f32 v[172:173], v[104:105], v[104:105]
	v_pk_mul_f32 v[110:111], v[110:111], v[110:111]
	v_pk_mul_f32 v[176:177], v[106:107], v[106:107]
	v_pk_fma_f32 v[118:119], v[118:119], v[174:175], v[142:143] op_sel_hi:[1,0,1]
	v_pk_fma_f32 v[116:117], v[116:117], v[174:175], v[140:141] op_sel_hi:[1,0,1]
	v_pk_fma_f32 v[114:115], v[114:115], v[174:175], v[138:139] op_sel_hi:[1,0,1]
	v_pk_fma_f32 v[112:113], v[112:113], v[174:175], v[136:137] op_sel_hi:[1,0,1]
	v_cvt_pk_bf16_f32 v104, v124, v125
	v_cvt_pk_bf16_f32 v105, v126, v127
	v_cvt_pk_bf16_f32 v106, v120, v121
	v_cvt_pk_bf16_f32 v107, v122, v123
	v_cvt_pk_bf16_f32 v108, v108, v109
	v_cvt_pk_bf16_f32 v109, v110, v111
	v_cvt_pk_bf16_f32 v110, v172, v173
	v_cvt_pk_bf16_f32 v111, v176, v177
	v_addc_co_u32_e32 v163, vcc, 0, v161, vcc
	v_max_f32_e32 v116, 0, v116
	v_max_f32_e32 v112, 0, v112
	v_max_f32_e32 v117, 0, v117
	global_store_dwordx4 v[160:161], v[104:107], off
	global_store_dwordx4 v[162:163], v[108:111], off
	v_max_f32_e32 v113, 0, v113
	v_pk_mul_f32 v[104:105], v[116:117], v[116:117]
	v_max_f32_e32 v108, 0, v118
	v_max_f32_e32 v110, 0, v114
	v_max_f32_e32 v109, 0, v119
	v_max_f32_e32 v111, 0, v115
	v_pk_mul_f32 v[106:107], v[112:113], v[112:113]
	v_pk_mul_f32 v[108:109], v[108:109], v[108:109]
	v_pk_mul_f32 v[110:111], v[110:111], v[110:111]
	v_pk_fma_f32 v[100:101], v[100:101], v[174:175], v[132:133] op_sel_hi:[1,0,1]
	v_pk_fma_f32 v[96:97], v[96:97], v[174:175], v[128:129] op_sel_hi:[1,0,1]
	v_cvt_pk_bf16_f32 v104, v104, v105
	v_cvt_pk_bf16_f32 v105, v108, v109
	v_cvt_pk_bf16_f32 v106, v106, v107
	v_cvt_pk_bf16_f32 v107, v110, v111
	v_pk_fma_f32 v[102:103], v[102:103], v[174:175], v[134:135] op_sel_hi:[1,0,1]
	v_max_f32_e32 v100, 0, v100
	v_max_f32_e32 v96, 0, v96
	v_max_f32_e32 v101, 0, v101
	v_max_f32_e32 v97, 0, v97
	global_store_dwordx4 v[160:161], v[104:107], off offset:1024
	v_pk_mul_f32 v[100:101], v[100:101], v[100:101]
	v_pk_fma_f32 v[98:99], v[98:99], v[174:175], v[130:131] op_sel_hi:[1,0,1]
	v_pk_mul_f32 v[104:105], v[96:97], v[96:97]
	v_max_f32_e32 v96, 0, v102
	v_max_f32_e32 v97, 0, v103
	v_pk_mul_f32 v[102:103], v[96:97], v[96:97]
	v_cvt_pk_bf16_f32 v96, v100, v101
	ds_read2_b32 v[100:101], v170 offset0:32 offset1:48
	v_max_f32_e32 v98, 0, v98
	v_max_f32_e32 v99, 0, v99
	v_pk_mul_f32 v[106:107], v[98:99], v[98:99]
	v_cvt_pk_bf16_f32 v97, v102, v103
	s_waitcnt lgkmcnt(0)
	v_pk_fma_f32 v[88:89], v[88:89], v[100:101], v[136:137] op_sel_hi:[1,0,1]
	v_cvt_pk_bf16_f32 v98, v104, v105
	v_cvt_pk_bf16_f32 v99, v106, v107
	v_pk_fma_f32 v[94:95], v[94:95], v[100:101], v[142:143] op_sel_hi:[1,0,1]
	v_pk_fma_f32 v[92:93], v[92:93], v[100:101], v[140:141] op_sel_hi:[1,0,1]
	v_pk_fma_f32 v[90:91], v[90:91], v[100:101], v[138:139] op_sel_hi:[1,0,1]
	v_max_f32_e32 v88, 0, v88
	v_max_f32_e32 v89, 0, v89
	global_store_dwordx4 v[162:163], v[96:99], off offset:1024
	v_max_f32_e32 v92, 0, v92
	v_max_f32_e32 v93, 0, v93
	v_pk_mul_f32 v[96:97], v[88:89], v[88:89]
	v_max_f32_e32 v88, 0, v94
	v_max_f32_e32 v90, 0, v90
	v_max_f32_e32 v89, 0, v95
	v_max_f32_e32 v91, 0, v91
	v_pk_mul_f32 v[92:93], v[92:93], v[92:93]
	v_pk_mul_f32 v[94:95], v[88:89], v[88:89]
	v_pk_mul_f32 v[98:99], v[90:91], v[90:91]
	v_pk_fma_f32 v[80:81], v[80:81], v[100:101], v[128:129] op_sel_hi:[1,0,1]
	v_cvt_pk_bf16_f32 v88, v92, v93
	v_cvt_pk_bf16_f32 v89, v94, v95
	v_cvt_pk_bf16_f32 v90, v96, v97
	v_cvt_pk_bf16_f32 v91, v98, v99
	v_pk_fma_f32 v[86:87], v[86:87], v[100:101], v[134:135] op_sel_hi:[1,0,1]
	v_pk_fma_f32 v[84:85], v[84:85], v[100:101], v[132:133] op_sel_hi:[1,0,1]
	v_pk_fma_f32 v[82:83], v[82:83], v[100:101], v[130:131] op_sel_hi:[1,0,1]
	v_max_f32_e32 v80, 0, v80
	v_max_f32_e32 v81, 0, v81
	global_store_dwordx4 v[160:161], v[88:91], off offset:2048
	v_max_f32_e32 v84, 0, v84
	v_max_f32_e32 v85, 0, v85
	v_pk_mul_f32 v[88:89], v[80:81], v[80:81]
	v_max_f32_e32 v80, 0, v86
	v_max_f32_e32 v82, 0, v82
	v_max_f32_e32 v81, 0, v87
	v_max_f32_e32 v83, 0, v83
	v_pk_mul_f32 v[84:85], v[84:85], v[84:85]
	v_pk_mul_f32 v[86:87], v[80:81], v[80:81]
	v_pk_mul_f32 v[90:91], v[82:83], v[82:83]
	v_cvt_pk_bf16_f32 v80, v84, v85
	v_cvt_pk_bf16_f32 v81, v86, v87
	v_cvt_pk_bf16_f32 v82, v88, v89
	v_cvt_pk_bf16_f32 v83, v90, v91
	global_store_dwordx4 v[162:163], v[80:83], off offset:2048
	s_nop 1
	v_mov_b32_e32 v80, v101
	v_pk_fma_f32 v[72:73], v[72:73], v[80:81], v[136:137] op_sel_hi:[1,0,1]
	v_pk_fma_f32 v[78:79], v[78:79], v[80:81], v[142:143] op_sel_hi:[1,0,1]
	v_pk_fma_f32 v[76:77], v[76:77], v[80:81], v[140:141] op_sel_hi:[1,0,1]
	v_pk_fma_f32 v[74:75], v[74:75], v[80:81], v[138:139] op_sel_hi:[1,0,1]
	v_max_f32_e32 v72, 0, v72
	v_max_f32_e32 v73, 0, v73
	v_max_f32_e32 v76, 0, v76
	v_max_f32_e32 v77, 0, v77
	v_pk_mul_f32 v[82:83], v[72:73], v[72:73]
	v_max_f32_e32 v72, 0, v78
	v_max_f32_e32 v74, 0, v74
	v_max_f32_e32 v73, 0, v79
	v_max_f32_e32 v75, 0, v75
	v_pk_mul_f32 v[76:77], v[76:77], v[76:77]
	v_pk_mul_f32 v[78:79], v[72:73], v[72:73]
	v_pk_mul_f32 v[84:85], v[74:75], v[74:75]
	v_pk_fma_f32 v[68:69], v[68:69], v[80:81], v[132:133] op_sel_hi:[1,0,1]
	v_pk_fma_f32 v[64:65], v[64:65], v[80:81], v[128:129] op_sel_hi:[1,0,1]
	v_cvt_pk_bf16_f32 v72, v76, v77
	v_cvt_pk_bf16_f32 v73, v78, v79
	v_cvt_pk_bf16_f32 v74, v82, v83
	v_cvt_pk_bf16_f32 v75, v84, v85
	v_pk_fma_f32 v[70:71], v[70:71], v[80:81], v[134:135] op_sel_hi:[1,0,1]
	v_max_f32_e32 v68, 0, v68
	v_max_f32_e32 v64, 0, v64
	v_max_f32_e32 v69, 0, v69
	v_max_f32_e32 v65, 0, v65
	global_store_dwordx4 v[160:161], v[72:75], off offset:3072
	v_pk_mul_f32 v[68:69], v[68:69], v[68:69]
	v_pk_fma_f32 v[66:67], v[66:67], v[80:81], v[130:131] op_sel_hi:[1,0,1]
	v_pk_mul_f32 v[72:73], v[64:65], v[64:65]
	v_max_f32_e32 v64, 0, v70
	v_max_f32_e32 v65, 0, v71
	v_pk_mul_f32 v[70:71], v[64:65], v[64:65]
	v_cvt_pk_bf16_f32 v64, v68, v69
	ds_read2_b32 v[68:69], v170 offset0:128 offset1:144
	v_max_f32_e32 v66, 0, v66
	v_max_f32_e32 v67, 0, v67
	v_pk_mul_f32 v[74:75], v[66:67], v[66:67]
	v_cvt_pk_bf16_f32 v65, v70, v71
	s_waitcnt lgkmcnt(0)
	v_pk_fma_f32 v[60:61], v[60:61], v[68:69], v[140:141] op_sel_hi:[1,0,1]
	v_pk_fma_f32 v[56:57], v[56:57], v[68:69], v[136:137] op_sel_hi:[1,0,1]
	v_cvt_pk_bf16_f32 v66, v72, v73
	v_cvt_pk_bf16_f32 v67, v74, v75
	v_pk_fma_f32 v[62:63], v[62:63], v[68:69], v[142:143] op_sel_hi:[1,0,1]
	v_pk_fma_f32 v[58:59], v[58:59], v[68:69], v[138:139] op_sel_hi:[1,0,1]
	v_max_f32_e32 v60, 0, v60
	v_max_f32_e32 v56, 0, v56
	v_max_f32_e32 v61, 0, v61
	v_max_f32_e32 v57, 0, v57
	global_store_dwordx4 v[162:163], v[64:67], off offset:3072
	v_pk_mul_f32 v[60:61], v[60:61], v[60:61]
	v_max_f32_e32 v58, 0, v58
	v_pk_mul_f32 v[64:65], v[56:57], v[56:57]
	v_max_f32_e32 v56, 0, v62
	v_max_f32_e32 v57, 0, v63
	v_max_f32_e32 v59, 0, v59
	v_pk_mul_f32 v[62:63], v[56:57], v[56:57]
	v_pk_mul_f32 v[66:67], v[58:59], v[58:59]
	v_cvt_pk_bf16_f32 v56, v60, v61
	v_add_co_u32_e32 v60, vcc, s51, v160
	v_pk_fma_f32 v[52:53], v[52:53], v[68:69], v[132:133] op_sel_hi:[1,0,1]
	v_pk_fma_f32 v[48:49], v[48:49], v[68:69], v[128:129] op_sel_hi:[1,0,1]
	v_cvt_pk_bf16_f32 v57, v62, v63
	v_cvt_pk_bf16_f32 v58, v64, v65
	v_cvt_pk_bf16_f32 v59, v66, v67
	v_addc_co_u32_e32 v61, vcc, 0, v161, vcc
	v_pk_fma_f32 v[54:55], v[54:55], v[68:69], v[134:135] op_sel_hi:[1,0,1]
	v_pk_fma_f32 v[50:51], v[50:51], v[68:69], v[130:131] op_sel_hi:[1,0,1]
	v_max_f32_e32 v52, 0, v52
	v_max_f32_e32 v48, 0, v48
	v_max_f32_e32 v53, 0, v53
	v_max_f32_e32 v49, 0, v49
	global_store_dwordx4 v[60:61], v[56:59], off
	v_pk_mul_f32 v[52:53], v[52:53], v[52:53]
	v_max_f32_e32 v50, 0, v50
	v_pk_mul_f32 v[56:57], v[48:49], v[48:49]
	v_max_f32_e32 v48, 0, v54
	v_max_f32_e32 v49, 0, v55
	v_max_f32_e32 v51, 0, v51
	v_pk_mul_f32 v[54:55], v[48:49], v[48:49]
	v_pk_mul_f32 v[58:59], v[50:51], v[50:51]
	v_cvt_pk_bf16_f32 v48, v52, v53
	v_add_co_u32_e32 v52, vcc, s50, v160
	v_cvt_pk_bf16_f32 v49, v54, v55
	v_cvt_pk_bf16_f32 v50, v56, v57
	v_cvt_pk_bf16_f32 v51, v58, v59
	v_addc_co_u32_e32 v53, vcc, 0, v161, vcc
	global_store_dwordx4 v[52:53], v[48:51], off
	s_andn2_b64 vcc, exec, s[4:5]
	s_mov_b64 s[4:5], -1
	v_mov_b32_e32 v48, v69
	v_pk_fma_f32 v[40:41], v[40:41], v[48:49], v[136:137] op_sel_hi:[1,0,1]
	v_pk_fma_f32 v[46:47], v[46:47], v[48:49], v[142:143] op_sel_hi:[1,0,1]
	v_pk_fma_f32 v[44:45], v[44:45], v[48:49], v[140:141] op_sel_hi:[1,0,1]
	v_pk_fma_f32 v[42:43], v[42:43], v[48:49], v[138:139] op_sel_hi:[1,0,1]
	v_max_f32_e32 v40, 0, v40
	v_max_f32_e32 v41, 0, v41
	v_max_f32_e32 v44, 0, v44
	v_max_f32_e32 v45, 0, v45
	v_pk_mul_f32 v[50:51], v[40:41], v[40:41]
	v_max_f32_e32 v40, 0, v46
	v_max_f32_e32 v42, 0, v42
	v_max_f32_e32 v41, 0, v47
	v_max_f32_e32 v43, 0, v43
	v_pk_mul_f32 v[44:45], v[44:45], v[44:45]
	v_pk_mul_f32 v[46:47], v[40:41], v[40:41]
	v_pk_mul_f32 v[54:55], v[42:43], v[42:43]
	v_pk_fma_f32 v[36:37], v[36:37], v[48:49], v[132:133] op_sel_hi:[1,0,1]
	v_pk_fma_f32 v[32:33], v[32:33], v[48:49], v[128:129] op_sel_hi:[1,0,1]
	v_cvt_pk_bf16_f32 v40, v44, v45
	v_cvt_pk_bf16_f32 v41, v46, v47
	v_cvt_pk_bf16_f32 v42, v50, v51
	v_cvt_pk_bf16_f32 v43, v54, v55
	v_pk_fma_f32 v[38:39], v[38:39], v[48:49], v[134:135] op_sel_hi:[1,0,1]
	v_max_f32_e32 v36, 0, v36
	v_max_f32_e32 v32, 0, v32
	v_max_f32_e32 v37, 0, v37
	v_max_f32_e32 v33, 0, v33
	global_store_dwordx4 v[60:61], v[40:43], off offset:1024
	v_pk_mul_f32 v[36:37], v[36:37], v[36:37]
	v_pk_fma_f32 v[34:35], v[34:35], v[48:49], v[130:131] op_sel_hi:[1,0,1]
	v_pk_mul_f32 v[40:41], v[32:33], v[32:33]
	v_max_f32_e32 v32, 0, v38
	v_max_f32_e32 v33, 0, v39
	v_pk_mul_f32 v[38:39], v[32:33], v[32:33]
	v_cvt_pk_bf16_f32 v32, v36, v37
	ds_read2_b32 v[36:37], v170 offset0:160 offset1:176
	v_max_f32_e32 v34, 0, v34
	v_max_f32_e32 v35, 0, v35
	v_pk_mul_f32 v[42:43], v[34:35], v[34:35]
	v_cvt_pk_bf16_f32 v33, v38, v39
	s_waitcnt lgkmcnt(0)
	v_pk_fma_f32 v[24:25], v[24:25], v[36:37], v[136:137] op_sel_hi:[1,0,1]
	v_cvt_pk_bf16_f32 v34, v40, v41
	v_cvt_pk_bf16_f32 v35, v42, v43
	v_pk_fma_f32 v[30:31], v[30:31], v[36:37], v[142:143] op_sel_hi:[1,0,1]
	v_pk_fma_f32 v[28:29], v[28:29], v[36:37], v[140:141] op_sel_hi:[1,0,1]
	v_pk_fma_f32 v[26:27], v[26:27], v[36:37], v[138:139] op_sel_hi:[1,0,1]
	v_max_f32_e32 v24, 0, v24
	v_max_f32_e32 v25, 0, v25
	global_store_dwordx4 v[52:53], v[32:35], off offset:1024
	v_max_f32_e32 v28, 0, v28
	v_max_f32_e32 v29, 0, v29
	v_pk_mul_f32 v[32:33], v[24:25], v[24:25]
	v_max_f32_e32 v24, 0, v30
	v_max_f32_e32 v26, 0, v26
	v_max_f32_e32 v25, 0, v31
	v_max_f32_e32 v27, 0, v27
	v_pk_mul_f32 v[28:29], v[28:29], v[28:29]
	v_pk_mul_f32 v[30:31], v[24:25], v[24:25]
	v_pk_mul_f32 v[34:35], v[26:27], v[26:27]
	v_pk_fma_f32 v[16:17], v[16:17], v[36:37], v[128:129] op_sel_hi:[1,0,1]
	v_cvt_pk_bf16_f32 v24, v28, v29
	v_cvt_pk_bf16_f32 v25, v30, v31
	v_cvt_pk_bf16_f32 v26, v32, v33
	v_cvt_pk_bf16_f32 v27, v34, v35
	v_pk_fma_f32 v[22:23], v[22:23], v[36:37], v[134:135] op_sel_hi:[1,0,1]
	v_pk_fma_f32 v[20:21], v[20:21], v[36:37], v[132:133] op_sel_hi:[1,0,1]
	v_pk_fma_f32 v[18:19], v[18:19], v[36:37], v[130:131] op_sel_hi:[1,0,1]
	v_max_f32_e32 v16, 0, v16
	v_max_f32_e32 v17, 0, v17
	global_store_dwordx4 v[60:61], v[24:27], off offset:2048
	v_max_f32_e32 v20, 0, v20
	v_max_f32_e32 v21, 0, v21
	v_pk_mul_f32 v[24:25], v[16:17], v[16:17]
	v_max_f32_e32 v16, 0, v22
	v_max_f32_e32 v18, 0, v18
	v_max_f32_e32 v17, 0, v23
	v_max_f32_e32 v19, 0, v19
	v_pk_mul_f32 v[20:21], v[20:21], v[20:21]
	v_pk_mul_f32 v[22:23], v[16:17], v[16:17]
	v_pk_mul_f32 v[26:27], v[18:19], v[18:19]
	v_cvt_pk_bf16_f32 v16, v20, v21
	v_cvt_pk_bf16_f32 v17, v22, v23
	v_cvt_pk_bf16_f32 v18, v24, v25
	v_cvt_pk_bf16_f32 v19, v26, v27
	global_store_dwordx4 v[52:53], v[16:19], off offset:2048
	s_nop 1
	v_mov_b32_e32 v16, v37
	v_pk_fma_f32 v[8:9], v[8:9], v[16:17], v[136:137] op_sel_hi:[1,0,1]
	v_pk_fma_f32 v[14:15], v[14:15], v[16:17], v[142:143] op_sel_hi:[1,0,1]
	v_pk_fma_f32 v[12:13], v[12:13], v[16:17], v[140:141] op_sel_hi:[1,0,1]
	v_pk_fma_f32 v[10:11], v[10:11], v[16:17], v[138:139] op_sel_hi:[1,0,1]
	v_max_f32_e32 v8, 0, v8
	v_max_f32_e32 v9, 0, v9
	v_max_f32_e32 v12, 0, v12
	v_max_f32_e32 v13, 0, v13
	v_pk_mul_f32 v[18:19], v[8:9], v[8:9]
	v_max_f32_e32 v8, 0, v14
	v_max_f32_e32 v10, 0, v10
	v_max_f32_e32 v9, 0, v15
	v_max_f32_e32 v11, 0, v11
	v_pk_mul_f32 v[12:13], v[12:13], v[12:13]
	v_pk_mul_f32 v[14:15], v[8:9], v[8:9]
	v_pk_mul_f32 v[20:21], v[10:11], v[10:11]
	v_pk_fma_f32 v[0:1], v[0:1], v[16:17], v[128:129] op_sel_hi:[1,0,1]
	v_cvt_pk_bf16_f32 v8, v12, v13
	v_cvt_pk_bf16_f32 v9, v14, v15
	v_cvt_pk_bf16_f32 v10, v18, v19
	v_cvt_pk_bf16_f32 v11, v20, v21
	v_pk_fma_f32 v[6:7], v[6:7], v[16:17], v[134:135] op_sel_hi:[1,0,1]
	v_pk_fma_f32 v[4:5], v[4:5], v[16:17], v[132:133] op_sel_hi:[1,0,1]
	v_pk_fma_f32 v[2:3], v[2:3], v[16:17], v[130:131] op_sel_hi:[1,0,1]
	v_max_f32_e32 v0, 0, v0
	v_max_f32_e32 v1, 0, v1
	global_store_dwordx4 v[60:61], v[8:11], off offset:3072
	v_max_f32_e32 v4, 0, v4
	v_max_f32_e32 v5, 0, v5
	v_pk_mul_f32 v[8:9], v[0:1], v[0:1]
	v_max_f32_e32 v0, 0, v6
	v_max_f32_e32 v2, 0, v2
	v_max_f32_e32 v1, 0, v7
	v_max_f32_e32 v3, 0, v3
	v_pk_mul_f32 v[4:5], v[4:5], v[4:5]
	v_pk_mul_f32 v[6:7], v[0:1], v[0:1]
	v_pk_mul_f32 v[10:11], v[2:3], v[2:3]
	v_cvt_pk_bf16_f32 v0, v4, v5
	v_cvt_pk_bf16_f32 v1, v6, v7
	v_cvt_pk_bf16_f32 v2, v8, v9
	v_cvt_pk_bf16_f32 v3, v10, v11
	global_store_dwordx4 v[52:53], v[0:3], off offset:3072
	s_cbranch_vccnz .LBB0_560
	s_andn2_b64 vcc, exec, s[8:9]
	s_cbranch_vccnz .LBB0_559
	s_branch .LBB0_559
.LBB0_574:
	s_waitcnt vmcnt(0)
	s_and_b64 vcc, exec, s[10:11]
	s_cbranch_vccz .Lff1_na
	s_barrier
.Lff1_na:
	v_readlane_b32 s68, v251, 22
	v_readlane_b32 s69, v251, 23
	s_barrier
.LBB0_575:
	s_cmp_gt_i32 s69, 9
	s_cselect_b64 s[4:5], -1, 0
	s_and_b64 s[6:7], s[6:7], s[4:5]
	s_andn2_b64 vcc, exec, s[6:7]
	s_cbranch_vccnz .LBB0_598
	s_waitcnt vmcnt(0)
	v_readlane_b32 s6, v251, 0
	v_readlane_b32 s7, v251, 1
	s_andn2_b64 vcc, exec, s[6:7]
	s_waitcnt vmcnt(0)
	s_barrier
	s_cbranch_vccnz .LBB0_597
	v_mbcnt_lo_u32_b32 v0, -1, 0
	v_mbcnt_hi_u32_b32 v0, -1, v0
	s_nop 0
	v_cmp_eq_u32_e32 vcc, 0, v0
	s_and_saveexec_b64 s[6:7], vcc
	s_cbranch_execz .LBB0_596
	v_readlane_b32 s8, v251, 24
	v_readlane_b32 s9, v251, 25
	s_andn2_b64 vcc, exec, s[8:9]
	s_cbranch_vccnz .LBB0_580
	buffer_wbl2 sc1
